# layer-1 shift images (cvec) computed in P1 on otherwise idle workgroups instead of in E(0) tail
# baseline (speedup 1.0000x reference)
.LBB0_111:
	s_load_dwordx2 s[4:5], s[0:1], 0xd8
	s_mov_b32 s59, 1
	s_waitcnt lgkmcnt(0)
	s_cmp_lt_i32 s4, 2
	s_cselect_b64 s[4:5], -1, 0
	s_and_b64 s[2:3], s[4:5], s[2:3]
	s_andn2_b64 vcc, exec, s[2:3]
	s_cbranch_vccnz .LBB0_155
	s_cmp_lt_i32 s59, 1
	s_cbranch_scc1 .LBB0_155
	s_add_u32 s14, s86, 0x100000
	v_readlane_b32 s36, v250, 3
	s_addc_u32 s15, s87, 0
	s_lshl_b32 s4, s36, 3
	s_add_i32 s60, s4, s76
	s_lshl_b32 s61, s33, 3
	s_cmpk_lt_i32 s60, 0x4200
	s_cselect_b64 s[16:17], -1, 0
	s_add_u32 s18, s86, 0x900000
	s_addc_u32 s19, s87, 0
	s_add_u32 s20, s86, 0x4c00000
	s_addc_u32 s21, s87, 0
	s_cmpk_eq_i32 s33, 0x100
	s_cselect_b64 s[22:23], -1, 0
	s_and_b32 s4, s4, 0x3f8
	s_add_i32 s29, s4, s76
	s_cmpk_lt_u32 s36, 0x80
	s_movk_i32 s100, 0x160
	s_cselect_b32 s100, 0x120, s100
	s_cmp_ge_u32 s29, s100
	s_cselect_b32 s101, 1, 0
	s_cselect_b32 s100, s100, 0
	s_sub_i32 s29, s29, s100
	s_bfe_i32 s4, s29, 0x10003
	s_lshl_b32 s5, s29, 3
	s_lshl_b32 s24, s29, 4
	s_and_b32 s4, s4, 0xb00
	s_and_b32 s5, s5, 0x3fffff80
	s_add_i32 s4, s4, s5
	s_and_b32 s5, s24, 0x70
	s_or_b32 s28, s4, s5
	s_add_i32 s4, s24, 0xfffff600
	s_lshl_b32 s6, s29, 7
	s_and_b32 s6, s6, 0x400
	s_lshr_b32 s4, s4, 1
	s_and_b32 s4, s4, 0x7fffff80
	s_or_b32 s5, s6, s5
	s_add_i32 s4, s4, s5
	s_lshl_b32 s5, s29, 5
	s_and_b32 s5, s5, 0xc0
	s_lshl_b32 s6, s29, 2
	s_and_b32 s7, s24, 0xf10
	s_and_b32 s6, s6, 32
	s_or_b32 s5, s7, s5
	s_addk_i32 s4, 0xa00
	s_or_b32 s5, s5, s6
	s_cmpk_lt_u32 s29, 0xa0
	s_load_dwordx4 s[8:11], s[0:1], 0x0
	s_load_dwordx2 s[12:13], s[0:1], 0x38
	s_cselect_b32 s30, s5, s4
	s_load_dwordx2 s[4:5], s[0:1], 0xa8
	s_load_dwordx2 s[6:7], s[0:1], 0x58
	s_cmpk_lt_u32 s36, 0x80
	s_movk_i32 s25, 0x1200
	s_cselect_b32 s31, 0, 0x3000
	s_cselect_b32 s62, s25, 0x1600
	s_waitcnt lgkmcnt(0)
	s_cselect_b32 s26, s6, s4
	s_mov_b32 s4, 0x500000
	s_cselect_b32 s27, s7, s5
	s_cselect_b32 s6, s4, 0x700000
	s_cselect_b32 s28, s30, s28
	s_add_u32 s30, s14, s31
	s_addc_u32 s31, s15, 0
	s_lshr_b32 s4, s62, 4
	s_mov_b32 s25, 0
	s_cmp_lt_u32 s29, s4
	s_cselect_b64 s[34:35], -1, 0
	s_lshl_b32 s63, s36, 9
	s_lshl_b32 s36, s33, 9
	s_lshl_b64 s[4:5], s[24:25], 2
	s_add_u32 s4, s86, s4
	s_addc_u32 s5, s87, s5
	s_add_u32 s38, s4, s6
	s_addc_u32 s39, s5, 0
	s_mul_i32 s100, s101, 0xcc000
	s_add_u32 s30, s30, s100
	s_addc_u32 s31, s31, 0
	s_lshl_b32 s100, s62, 12
	s_mul_i32 s100, s100, s101
	s_add_u32 s26, s26, s100
	s_addc_u32 s27, s27, 0
	s_mul_i32 s100, s62, 0x88
	s_mul_i32 s100, s100, s101
	s_add_u32 s38, s38, s100
	s_addc_u32 s39, s39, 0
	s_lshl_b32 s24, s62, 10
	s_lshl_b32 s40, s62, 2
	s_add_u32 s44, s86, 0xa80000
	s_addc_u32 s45, s87, 0
	s_ashr_i32 s37, s36, 31
	s_mov_b32 s29, s25
	s_mov_b32 s41, s25
	s_mul_i32 s42, s62, 0x64
	s_mov_b32 s43, s25
	s_lshl_b64 s[46:47], s[36:37], 2
	s_movk_i32 s37, 0x6000
	s_mov_b64 s[48:49], 0x1000
	s_movk_i32 s64, 0x1000
	v_mov_b32_e32 v83, 0
	s_movk_i32 s65, 0x810
	s_mov_b32 s66, 0x22000
	s_mov_b32 s67, 0x78787879
	s_mov_b32 s68, 0x21fff
	v_mov_b32_e32 v1, 0x4000
	v_mov_b32_e32 v90, 0x1000
	s_mov_b32 s69, s25
	s_branch .LBB0_115

.LBB0_1544:
	v_readlane_b32 s0, v254, 60
	v_readlane_b32 s1, v254, 61
	s_andn2_b64 vcc, exec, s[0:1]
	s_waitcnt lgkmcnt(0)
	s_barrier
	s_branch .LBB0_1596
	v_readlane_b32 s2, v253, 43
	v_readlane_b32 s3, v253, 44
	s_mov_b64 s[0:1], -1
	s_and_b64 vcc, exec, s[2:3]
	s_cbranch_vccz .LBB0_1568
	v_mov_b32_e32 v1, v0
	v_readlane_b32 s0, v253, 45
	v_lshlrev_b32_e32 v2, 1, v1
	v_ashrrev_i32_e32 v3, 31, v2
	v_readlane_b32 s1, v253, 46
	s_barrier
	s_nop 0
	v_lshl_add_u64 v[2:3], v[2:3], 2, s[0:1]
	v_add_co_u32_e32 v4, vcc, 0x6000, v2
	s_nop 1
	v_addc_co_u32_e32 v5, vcc, 0, v3, vcc
	s_waitcnt vmcnt(0)
	v_add_co_u32_e32 v6, vcc, 0xc000, v2
	s_mov_b32 s0, 0x30000
	s_nop 0
	v_addc_co_u32_e32 v7, vcc, 0, v3, vcc
	v_add_co_u32_e32 v8, vcc, 0x12000, v2
	s_nop 1
	v_addc_co_u32_e32 v9, vcc, 0, v3, vcc
	global_load_dwordx2 v[70:71], v[2:3], off
	global_load_dwordx2 v[68:69], v[4:5], off
	global_load_dwordx2 v[64:65], v[6:7], off
	global_load_dwordx2 v[58:59], v[8:9], off
	v_add_co_u32_e32 v4, vcc, 0x18000, v2
	s_nop 1
	v_addc_co_u32_e32 v5, vcc, 0, v3, vcc
	v_add_co_u32_e32 v6, vcc, 0x1e000, v2
	s_nop 1
	v_addc_co_u32_e32 v7, vcc, 0, v3, vcc
	v_add_co_u32_e32 v8, vcc, 0x24000, v2
	s_nop 1
	v_addc_co_u32_e32 v9, vcc, 0, v3, vcc
	v_add_co_u32_e32 v10, vcc, 0x2a000, v2
	s_nop 1
	v_addc_co_u32_e32 v11, vcc, 0, v3, vcc
	global_load_dwordx2 v[66:67], v[4:5], off
	global_load_dwordx2 v[62:63], v[6:7], off
	global_load_dwordx2 v[56:57], v[8:9], off
	global_load_dwordx2 v[50:51], v[10:11], off
	v_add_co_u32_e32 v4, vcc, s0, v2
	s_mov_b32 s0, 0x60000
	s_nop 0
	v_addc_co_u32_e32 v5, vcc, 0, v3, vcc
	v_add_co_u32_e32 v6, vcc, 0x36000, v2
	s_nop 1
	v_addc_co_u32_e32 v7, vcc, 0, v3, vcc
	v_add_co_u32_e32 v8, vcc, 0x3c000, v2
	s_nop 1
	v_addc_co_u32_e32 v9, vcc, 0, v3, vcc
	v_add_co_u32_e32 v10, vcc, 0x42000, v2
	s_nop 1
	v_addc_co_u32_e32 v11, vcc, 0, v3, vcc
	global_load_dwordx2 v[60:61], v[4:5], off
	global_load_dwordx2 v[54:55], v[6:7], off
	global_load_dwordx2 v[48:49], v[8:9], off
	global_load_dwordx2 v[42:43], v[10:11], off
	v_add_co_u32_e32 v4, vcc, 0x48000, v2
	s_nop 1
	v_addc_co_u32_e32 v5, vcc, 0, v3, vcc
	v_add_co_u32_e32 v6, vcc, 0x4e000, v2
	s_nop 1
	v_addc_co_u32_e32 v7, vcc, 0, v3, vcc
	v_add_co_u32_e32 v8, vcc, 0x54000, v2
	s_nop 1
	v_addc_co_u32_e32 v9, vcc, 0, v3, vcc
	v_add_co_u32_e32 v10, vcc, 0x5a000, v2
	s_nop 1
	v_addc_co_u32_e32 v11, vcc, 0, v3, vcc
	global_load_dwordx2 v[52:53], v[4:5], off
	global_load_dwordx2 v[46:47], v[6:7], off
	global_load_dwordx2 v[40:41], v[8:9], off
	global_load_dwordx2 v[34:35], v[10:11], off
	v_add_co_u32_e32 v4, vcc, s0, v2
	s_mov_b32 s0, 0xc0000
	s_nop 0
	v_addc_co_u32_e32 v5, vcc, 0, v3, vcc
	v_add_co_u32_e32 v6, vcc, 0x66000, v2
	s_nop 1
	v_addc_co_u32_e32 v7, vcc, 0, v3, vcc
	v_add_co_u32_e32 v8, vcc, 0x6c000, v2
	s_nop 1
	v_addc_co_u32_e32 v9, vcc, 0, v3, vcc
	v_add_co_u32_e32 v10, vcc, 0x72000, v2
	s_nop 1
	v_addc_co_u32_e32 v11, vcc, 0, v3, vcc
	global_load_dwordx2 v[44:45], v[4:5], off
	global_load_dwordx2 v[38:39], v[6:7], off
	global_load_dwordx2 v[32:33], v[8:9], off
	global_load_dwordx2 v[26:27], v[10:11], off
	v_add_co_u32_e32 v4, vcc, 0x78000, v2
	s_nop 1
	v_addc_co_u32_e32 v5, vcc, 0, v3, vcc
	v_add_co_u32_e32 v6, vcc, 0x7e000, v2
	s_nop 1
	v_addc_co_u32_e32 v7, vcc, 0, v3, vcc
	v_add_co_u32_e32 v8, vcc, 0x84000, v2
	s_nop 1
	v_addc_co_u32_e32 v9, vcc, 0, v3, vcc
	v_add_co_u32_e32 v10, vcc, 0x8a000, v2
	s_nop 1
	v_addc_co_u32_e32 v11, vcc, 0, v3, vcc
	global_load_dwordx2 v[36:37], v[4:5], off
	global_load_dwordx2 v[30:31], v[6:7], off
	global_load_dwordx2 v[24:25], v[8:9], off
	global_load_dwordx2 v[18:19], v[10:11], off
	v_add_co_u32_e32 v4, vcc, 0x90000, v2
	s_nop 1
	v_addc_co_u32_e32 v5, vcc, 0, v3, vcc
	v_add_co_u32_e32 v6, vcc, 0x96000, v2
	s_nop 1
	v_addc_co_u32_e32 v7, vcc, 0, v3, vcc
	v_add_co_u32_e32 v8, vcc, 0x9c000, v2
	s_nop 1
	v_addc_co_u32_e32 v9, vcc, 0, v3, vcc
	v_add_co_u32_e32 v10, vcc, 0xa2000, v2
	s_nop 1
	v_addc_co_u32_e32 v11, vcc, 0, v3, vcc
	global_load_dwordx2 v[28:29], v[4:5], off
	global_load_dwordx2 v[22:23], v[6:7], off
	global_load_dwordx2 v[16:17], v[8:9], off
	s_nop 0
	global_load_dwordx2 v[10:11], v[10:11], off
	v_add_co_u32_e32 v4, vcc, 0xa8000, v2
	s_nop 1
	v_addc_co_u32_e32 v5, vcc, 0, v3, vcc
	v_add_co_u32_e32 v6, vcc, 0xae000, v2
	s_nop 1
	v_addc_co_u32_e32 v7, vcc, 0, v3, vcc
	v_add_co_u32_e32 v8, vcc, 0xb4000, v2
	s_nop 1
	v_addc_co_u32_e32 v9, vcc, 0, v3, vcc
	v_add_co_u32_e32 v72, vcc, 0xba000, v2
	s_nop 1
	v_addc_co_u32_e32 v73, vcc, 0, v3, vcc
	global_load_dwordx2 v[20:21], v[4:5], off
	global_load_dwordx2 v[12:13], v[6:7], off
	s_nop 0
	global_load_dwordx2 v[8:9], v[8:9], off
	s_nop 0
	global_load_dwordx2 v[4:5], v[72:73], off
	v_add_co_u32_e32 v6, vcc, s0, v2
	s_nop 1
	v_addc_co_u32_e32 v7, vcc, 0, v3, vcc
	v_add_co_u32_e32 v2, vcc, 0xc6000, v2
	s_nop 1
	v_addc_co_u32_e32 v3, vcc, 0, v3, vcc
	global_load_dwordx2 v[6:7], v[6:7], off
	s_nop 0
	global_load_dwordx2 v[2:3], v[2:3], off
	s_waitcnt vmcnt(33)
	v_cvt_pk_bf16_f32 v14, v70, v71
	v_lshl_add_u32 v1, v1, 2, 0
	v_lshlrev_b32_e32 v72, 16, v14
	v_sub_f32_e32 v70, v70, v72
	v_and_b32_e32 v72, 0xffff0000, v14
	v_sub_f32_e32 v71, v71, v72
	v_cvt_pk_bf16_f32 v70, v70, v71
	ds_write_b32 v1, v14
	v_add_u32_e32 v14, 0x11220, v1
	ds_write_b32 v14, v70
	s_waitcnt vmcnt(32)
	v_cvt_pk_bf16_f32 v14, v68, v69
	v_readlane_b32 s0, v253, 47
	v_lshlrev_b32_e32 v70, 16, v14
	v_sub_f32_e32 v68, v68, v70
	v_and_b32_e32 v70, 0xffff0000, v14
	v_sub_f32_e32 v69, v69, v70
	v_cvt_pk_bf16_f32 v68, v68, v69
	ds_write_b32 v1, v14 offset:2064
	v_add_u32_e32 v14, 0x11a30, v1
	ds_write_b32 v14, v68
	s_waitcnt vmcnt(31)
	v_cvt_pk_bf16_f32 v14, v64, v65
	v_readlane_b32 s1, v253, 48
	v_lshlrev_b32_e32 v68, 16, v14
	v_sub_f32_e32 v64, v64, v68
	v_and_b32_e32 v68, 0xffff0000, v14
	v_sub_f32_e32 v65, v65, v68
	v_cvt_pk_bf16_f32 v64, v64, v65
	ds_write_b32 v1, v14 offset:4128
	v_add_u32_e32 v14, 0x12240, v1
	ds_write_b32 v14, v64
	s_waitcnt vmcnt(30)
	v_cvt_pk_bf16_f32 v14, v58, v59
	s_andn2_b64 vcc, exec, s[0:1]
	v_lshlrev_b32_e32 v64, 16, v14
	v_sub_f32_e32 v58, v58, v64
	v_and_b32_e32 v64, 0xffff0000, v14
	v_sub_f32_e32 v59, v59, v64
	v_cvt_pk_bf16_f32 v58, v58, v59
	ds_write_b32 v1, v14 offset:6192
	v_add_u32_e32 v14, 0x12a50, v1
	ds_write_b32 v14, v58
	s_waitcnt vmcnt(29)
	v_cvt_pk_bf16_f32 v14, v66, v67
	s_nop 0
	v_lshlrev_b32_e32 v58, 16, v14
	v_sub_f32_e32 v58, v66, v58
	v_and_b32_e32 v59, 0xffff0000, v14
	v_sub_f32_e32 v59, v67, v59
	v_cvt_pk_bf16_f32 v58, v58, v59
	ds_write_b32 v1, v14 offset:8256
	v_add_u32_e32 v14, 0x13260, v1
	ds_write_b32 v14, v58
	s_waitcnt vmcnt(28)
	v_cvt_pk_bf16_f32 v14, v62, v63
	s_nop 0
	v_lshlrev_b32_e32 v58, 16, v14
	v_sub_f32_e32 v58, v62, v58
	v_and_b32_e32 v59, 0xffff0000, v14
	v_sub_f32_e32 v59, v63, v59
	v_cvt_pk_bf16_f32 v58, v58, v59
	ds_write_b32 v1, v14 offset:10320
	v_add_u32_e32 v14, 0x13a70, v1
	ds_write_b32 v14, v58
	s_waitcnt vmcnt(27)
	v_cvt_pk_bf16_f32 v14, v56, v57
	s_nop 0
	v_lshlrev_b32_e32 v58, 16, v14
	v_sub_f32_e32 v56, v56, v58
	v_and_b32_e32 v58, 0xffff0000, v14
	v_sub_f32_e32 v57, v57, v58
	v_cvt_pk_bf16_f32 v56, v56, v57
	ds_write_b32 v1, v14 offset:12384
	v_add_u32_e32 v14, 0x14280, v1
	ds_write_b32 v14, v56
	s_waitcnt vmcnt(26)
	v_cvt_pk_bf16_f32 v14, v50, v51
	s_nop 0
	v_lshlrev_b32_e32 v56, 16, v14
	v_sub_f32_e32 v50, v50, v56
	v_and_b32_e32 v56, 0xffff0000, v14
	v_sub_f32_e32 v51, v51, v56
	v_cvt_pk_bf16_f32 v50, v50, v51
	ds_write_b32 v1, v14 offset:14448
	v_add_u32_e32 v14, 0x14a90, v1
	ds_write_b32 v14, v50
	s_waitcnt vmcnt(25)
	v_cvt_pk_bf16_f32 v14, v60, v61
	s_nop 0
	v_lshlrev_b32_e32 v50, 16, v14
	v_sub_f32_e32 v50, v60, v50
	v_and_b32_e32 v51, 0xffff0000, v14
	v_sub_f32_e32 v51, v61, v51
	v_cvt_pk_bf16_f32 v50, v50, v51
	ds_write_b32 v1, v14 offset:16512
	v_add_u32_e32 v14, 0x152a0, v1
	ds_write_b32 v14, v50
	s_waitcnt vmcnt(24)
	v_cvt_pk_bf16_f32 v14, v54, v55
	s_nop 0
	v_lshlrev_b32_e32 v50, 16, v14
	v_sub_f32_e32 v50, v54, v50
	v_and_b32_e32 v51, 0xffff0000, v14
	v_sub_f32_e32 v51, v55, v51
	v_cvt_pk_bf16_f32 v50, v50, v51
	ds_write_b32 v1, v14 offset:18576
	v_add_u32_e32 v14, 0x15ab0, v1
	ds_write_b32 v14, v50
	s_waitcnt vmcnt(23)
	v_cvt_pk_bf16_f32 v14, v48, v49
	s_nop 0
	v_lshlrev_b32_e32 v50, 16, v14
	v_sub_f32_e32 v48, v48, v50
	v_and_b32_e32 v50, 0xffff0000, v14
	v_sub_f32_e32 v49, v49, v50
	v_cvt_pk_bf16_f32 v48, v48, v49
	ds_write_b32 v1, v14 offset:20640
	v_add_u32_e32 v14, 0x162c0, v1
	ds_write_b32 v14, v48
	s_waitcnt vmcnt(22)
	v_cvt_pk_bf16_f32 v14, v42, v43
	s_nop 0
	v_lshlrev_b32_e32 v48, 16, v14
	v_sub_f32_e32 v42, v42, v48
	v_and_b32_e32 v48, 0xffff0000, v14
	v_sub_f32_e32 v43, v43, v48
	v_cvt_pk_bf16_f32 v42, v42, v43
	ds_write_b32 v1, v14 offset:22704
	v_add_u32_e32 v14, 0x16ad0, v1
	ds_write_b32 v14, v42
	s_waitcnt vmcnt(21)
	v_cvt_pk_bf16_f32 v14, v52, v53
	s_nop 0
	v_lshlrev_b32_e32 v42, 16, v14
	v_sub_f32_e32 v42, v52, v42
	v_and_b32_e32 v43, 0xffff0000, v14
	v_sub_f32_e32 v43, v53, v43
	v_cvt_pk_bf16_f32 v42, v42, v43
	ds_write_b32 v1, v14 offset:24768
	v_add_u32_e32 v14, 0x172e0, v1
	ds_write_b32 v14, v42
	s_waitcnt vmcnt(20)
	v_cvt_pk_bf16_f32 v14, v46, v47
	s_nop 0
	v_lshlrev_b32_e32 v42, 16, v14
	v_sub_f32_e32 v42, v46, v42
	v_and_b32_e32 v43, 0xffff0000, v14
	v_sub_f32_e32 v43, v47, v43
	v_cvt_pk_bf16_f32 v42, v42, v43
	ds_write_b32 v1, v14 offset:26832
	v_add_u32_e32 v14, 0x17af0, v1
	ds_write_b32 v14, v42
	s_waitcnt vmcnt(19)
	v_cvt_pk_bf16_f32 v14, v40, v41
	s_nop 0
	v_lshlrev_b32_e32 v42, 16, v14
	v_sub_f32_e32 v40, v40, v42
	v_and_b32_e32 v42, 0xffff0000, v14
	v_sub_f32_e32 v41, v41, v42
	v_cvt_pk_bf16_f32 v40, v40, v41
	ds_write_b32 v1, v14 offset:28896
	v_add_u32_e32 v14, 0x18300, v1
	ds_write_b32 v14, v40
	s_waitcnt vmcnt(18)
	v_cvt_pk_bf16_f32 v14, v34, v35
	s_nop 0
	v_lshlrev_b32_e32 v40, 16, v14
	v_sub_f32_e32 v34, v34, v40
	v_and_b32_e32 v40, 0xffff0000, v14
	v_sub_f32_e32 v35, v35, v40
	v_cvt_pk_bf16_f32 v34, v34, v35
	ds_write_b32 v1, v14 offset:30960
	v_add_u32_e32 v14, 0x18b10, v1
	ds_write_b32 v14, v34
	s_waitcnt vmcnt(17)
	v_cvt_pk_bf16_f32 v14, v44, v45
	s_nop 0
	v_lshlrev_b32_e32 v34, 16, v14
	v_sub_f32_e32 v34, v44, v34
	v_and_b32_e32 v35, 0xffff0000, v14
	v_sub_f32_e32 v35, v45, v35
	v_cvt_pk_bf16_f32 v34, v34, v35
	ds_write_b32 v1, v14 offset:33024
	v_add_u32_e32 v14, 0x19320, v1
	ds_write_b32 v14, v34
	s_waitcnt vmcnt(16)
	v_cvt_pk_bf16_f32 v14, v38, v39
	s_nop 0
	v_lshlrev_b32_e32 v34, 16, v14
	v_sub_f32_e32 v34, v38, v34
	v_and_b32_e32 v35, 0xffff0000, v14
	v_sub_f32_e32 v35, v39, v35
	v_cvt_pk_bf16_f32 v34, v34, v35
	ds_write_b32 v1, v14 offset:35088
	v_add_u32_e32 v14, 0x19b30, v1
	ds_write_b32 v14, v34
	s_waitcnt vmcnt(15)
	v_cvt_pk_bf16_f32 v14, v32, v33
	s_nop 0
	v_lshlrev_b32_e32 v34, 16, v14
	v_sub_f32_e32 v32, v32, v34
	v_and_b32_e32 v34, 0xffff0000, v14
	v_sub_f32_e32 v33, v33, v34
	v_cvt_pk_bf16_f32 v32, v32, v33
	ds_write_b32 v1, v14 offset:37152
	v_add_u32_e32 v14, 0x1a340, v1
	ds_write_b32 v14, v32
	s_waitcnt vmcnt(14)
	v_cvt_pk_bf16_f32 v14, v26, v27
	s_nop 0
	v_lshlrev_b32_e32 v32, 16, v14
	v_sub_f32_e32 v26, v26, v32
	v_and_b32_e32 v32, 0xffff0000, v14
	v_sub_f32_e32 v27, v27, v32
	v_cvt_pk_bf16_f32 v26, v26, v27
	ds_write_b32 v1, v14 offset:39216
	v_add_u32_e32 v14, 0x1ab50, v1
	ds_write_b32 v14, v26
	s_waitcnt vmcnt(13)
	v_cvt_pk_bf16_f32 v14, v36, v37
	s_nop 0
	v_lshlrev_b32_e32 v26, 16, v14
	v_sub_f32_e32 v26, v36, v26
	v_and_b32_e32 v27, 0xffff0000, v14
	v_sub_f32_e32 v27, v37, v27
	v_cvt_pk_bf16_f32 v26, v26, v27
	ds_write_b32 v1, v14 offset:41280
	v_add_u32_e32 v14, 0x1b360, v1
	ds_write_b32 v14, v26
	s_waitcnt vmcnt(12)
	v_cvt_pk_bf16_f32 v14, v30, v31
	s_nop 0
	v_lshlrev_b32_e32 v26, 16, v14
	v_sub_f32_e32 v26, v30, v26
	v_and_b32_e32 v27, 0xffff0000, v14
	v_sub_f32_e32 v27, v31, v27
	v_cvt_pk_bf16_f32 v26, v26, v27
	ds_write_b32 v1, v14 offset:43344
	v_add_u32_e32 v14, 0x1bb70, v1
	ds_write_b32 v14, v26
	s_waitcnt vmcnt(11)
	v_cvt_pk_bf16_f32 v14, v24, v25
	s_nop 0
	v_lshlrev_b32_e32 v26, 16, v14
	v_sub_f32_e32 v24, v24, v26
	v_and_b32_e32 v26, 0xffff0000, v14
	v_sub_f32_e32 v25, v25, v26
	v_cvt_pk_bf16_f32 v24, v24, v25
	ds_write_b32 v1, v14 offset:45408
	v_add_u32_e32 v14, 0x1c380, v1
	ds_write_b32 v14, v24
	s_waitcnt vmcnt(10)
	v_cvt_pk_bf16_f32 v14, v18, v19
	s_nop 0
	v_lshlrev_b32_e32 v24, 16, v14
	v_sub_f32_e32 v18, v18, v24
	v_and_b32_e32 v24, 0xffff0000, v14
	v_sub_f32_e32 v19, v19, v24
	v_cvt_pk_bf16_f32 v18, v18, v19
	ds_write_b32 v1, v14 offset:47472
	v_add_u32_e32 v14, 0x1cb90, v1
	ds_write_b32 v14, v18
	s_waitcnt vmcnt(9)
	v_cvt_pk_bf16_f32 v14, v28, v29
	s_nop 0
	v_lshlrev_b32_e32 v18, 16, v14
	v_sub_f32_e32 v18, v28, v18
	v_and_b32_e32 v19, 0xffff0000, v14
	v_sub_f32_e32 v19, v29, v19
	v_cvt_pk_bf16_f32 v18, v18, v19
	ds_write_b32 v1, v14 offset:49536
	v_add_u32_e32 v14, 0x1d3a0, v1
	ds_write_b32 v14, v18
	s_waitcnt vmcnt(8)
	v_cvt_pk_bf16_f32 v14, v22, v23
	s_nop 0
	v_lshlrev_b32_e32 v18, 16, v14
	v_sub_f32_e32 v18, v22, v18
	v_and_b32_e32 v19, 0xffff0000, v14
	v_sub_f32_e32 v19, v23, v19
	v_cvt_pk_bf16_f32 v18, v18, v19
	ds_write_b32 v1, v14 offset:51600
	v_add_u32_e32 v14, 0x1dbb0, v1
	ds_write_b32 v14, v18
	s_waitcnt vmcnt(7)
	v_cvt_pk_bf16_f32 v14, v16, v17
	s_nop 0
	v_lshlrev_b32_e32 v18, 16, v14
	v_sub_f32_e32 v16, v16, v18
	v_and_b32_e32 v18, 0xffff0000, v14
	v_sub_f32_e32 v17, v17, v18
	v_cvt_pk_bf16_f32 v16, v16, v17
	ds_write_b32 v1, v14 offset:53664
	v_add_u32_e32 v14, 0x1e3c0, v1
	ds_write_b32 v14, v16
	s_waitcnt vmcnt(6)
	v_cvt_pk_bf16_f32 v14, v10, v11
	s_nop 0
	v_lshlrev_b32_e32 v16, 16, v14
	v_sub_f32_e32 v10, v10, v16
	v_and_b32_e32 v16, 0xffff0000, v14
	v_sub_f32_e32 v11, v11, v16
	v_cvt_pk_bf16_f32 v10, v10, v11
	v_add_u32_e32 v11, 0x1ebd0, v1
	ds_write_b32 v1, v14 offset:55728
	ds_write_b32 v11, v10
	s_waitcnt vmcnt(5)
	v_cvt_pk_bf16_f32 v10, v20, v21
	s_nop 0
	v_lshlrev_b32_e32 v11, 16, v10
	v_sub_f32_e32 v11, v20, v11
	v_and_b32_e32 v14, 0xffff0000, v10
	v_sub_f32_e32 v14, v21, v14
	v_cvt_pk_bf16_f32 v11, v11, v14
	ds_write_b32 v1, v10 offset:57792
	v_add_u32_e32 v10, 0x1f3e0, v1
	ds_write_b32 v10, v11
	s_waitcnt vmcnt(4)
	v_cvt_pk_bf16_f32 v10, v12, v13
	s_nop 0
	v_lshlrev_b32_e32 v11, 16, v10
	v_sub_f32_e32 v11, v12, v11
	v_and_b32_e32 v12, 0xffff0000, v10
	v_sub_f32_e32 v12, v13, v12
	v_cvt_pk_bf16_f32 v11, v11, v12
	ds_write_b32 v1, v10 offset:59856
	v_add_u32_e32 v10, 0x1fbf0, v1
	ds_write_b32 v10, v11
	s_waitcnt vmcnt(3)
	v_cvt_pk_bf16_f32 v10, v8, v9
	s_nop 0
	v_lshlrev_b32_e32 v11, 16, v10
	v_sub_f32_e32 v8, v8, v11
	v_and_b32_e32 v11, 0xffff0000, v10
	v_sub_f32_e32 v9, v9, v11
	v_cvt_pk_bf16_f32 v8, v8, v9
	v_add_u32_e32 v9, 0x20400, v1
	ds_write_b32 v1, v10 offset:61920
	ds_write_b32 v9, v8
	s_waitcnt vmcnt(2)
	v_cvt_pk_bf16_f32 v8, v4, v5
	s_nop 0
	v_lshlrev_b32_e32 v9, 16, v8
	v_sub_f32_e32 v4, v4, v9
	v_and_b32_e32 v9, 0xffff0000, v8
	v_sub_f32_e32 v5, v5, v9
	v_cvt_pk_bf16_f32 v4, v4, v5
	v_add_u32_e32 v5, 0x20c10, v1
	ds_write_b32 v1, v8 offset:63984
	ds_write_b32 v5, v4
	s_waitcnt vmcnt(1)
	v_cvt_pk_bf16_f32 v4, v6, v7
	s_nop 0
	v_lshlrev_b32_e32 v5, 16, v4
	v_sub_f32_e32 v5, v6, v5
	v_and_b32_e32 v6, 0xffff0000, v4
	v_sub_f32_e32 v6, v7, v6
	v_cvt_pk_bf16_f32 v5, v5, v6
	v_add_u32_e32 v6, 0x10200, v1
	ds_write_b32 v6, v4
	v_add_u32_e32 v4, 0x21420, v1
	ds_write_b32 v4, v5
	s_waitcnt vmcnt(0)
	v_cvt_pk_bf16_f32 v4, v2, v3
	s_nop 0
	v_lshlrev_b32_e32 v5, 16, v4
	v_sub_f32_e32 v2, v2, v5
	v_and_b32_e32 v5, 0xffff0000, v4
	v_sub_f32_e32 v3, v3, v5
	v_cvt_pk_bf16_f32 v2, v2, v3
	v_add_u32_e32 v3, 0x10a10, v1
	v_add_u32_e32 v1, 0x21c30, v1
	ds_write_b32 v3, v4
	ds_write_b32 v1, v2
	s_waitcnt lgkmcnt(0)
	v_mov_b32_e32 v1, v227
	s_waitcnt lgkmcnt(0)
	s_barrier
	s_cbranch_vccnz .LBB0_1567
	v_ashrrev_i32_e32 v2, 4, v1
	v_lshlrev_b32_e32 v3, 3, v2
	s_movk_i32 s4, 0x5800
	v_lshlrev_b32_e32 v6, 2, v2
	v_cmp_gt_i32_e32 vcc, 9, v2
	v_cmp_gt_i32_e64 s[42:43], 5, v2
	v_cmp_gt_i32_e64 s[44:45], 4, v2
	v_cmp_gt_i32_e64 s[46:47], 1, v2
	v_cmp_gt_i32_e64 s[48:49], 0, v2
	v_mad_i64_i32 v[2:3], s[2:3], v3, s4, 0
	v_and_b32_e32 v4, 15, v1
	v_readlane_b32 s2, v253, 49
	v_or_b32_e32 v7, 1, v6
	v_or_b32_e32 v8, 2, v6
	v_or_b32_e32 v9, 3, v6
	v_add_u32_e32 v10, 16, v6
	v_add_u32_e32 v11, 17, v6
	v_add_u32_e32 v12, 18, v6
	v_add_u32_e32 v13, 19, v6
	v_add_u32_e32 v16, 32, v6
	v_add_u32_e32 v17, 33, v6
	v_add_u32_e32 v18, 34, v6
	v_add_u32_e32 v19, 35, v6
	v_lshlrev_b32_e32 v14, 2, v4
	v_readlane_b32 s3, v253, 50
	v_or_b32_e32 v5, 32, v4
	v_min_u32_e32 v5, 33, v5
	v_lshl_add_u64 v[28:29], s[2:3], 0, v[14:15]
	v_mad_i64_i32 v[30:31], s[2:3], v6, s4, 0
	v_mad_i64_i32 v[32:33], s[2:3], v7, s4, 0
	v_mad_i64_i32 v[34:35], s[2:3], v8, s4, 0
	v_mad_i64_i32 v[36:37], s[2:3], v9, s4, 0
	v_mad_i64_i32 v[38:39], s[2:3], v11, s4, 0
	v_mad_i64_i32 v[40:41], s[2:3], v10, s4, 0
	v_mad_i64_i32 v[42:43], s[2:3], v13, s4, 0
	v_mad_i64_i32 v[44:45], s[2:3], v12, s4, 0
	v_mad_i64_i32 v[46:47], s[2:3], v17, s4, 0
	v_mad_i64_i32 v[48:49], s[2:3], v16, s4, 0
	v_mad_i64_i32 v[50:51], s[2:3], v19, s4, 0
	v_mad_i64_i32 v[52:53], s[2:3], v18, s4, 0
	s_movk_i32 s2, 0x810
	s_nop 0
	v_mad_u32_u24 v58, v4, s2, 0
	v_mad_u32_u24 v59, v5, s2, 0
	v_readlane_b32 s2, v254, 39
	v_or_b32_e32 v2, v2, v14
	v_readlane_b32 s3, v254, 40
	v_and_b32_e32 v1, -16, v1
	v_cmp_gt_i32_e64 s[0:1], 34, v7
	v_cmp_gt_i32_e64 s[38:39], 34, v8
	v_cmp_gt_i32_e64 s[40:41], 34, v9
	v_lshl_add_u64 v[54:55], s[2:3], 0, v[2:3]
	v_readlane_b32 s8, v254, 43
	v_readlane_b32 s9, v254, 41
	v_readlane_b32 s10, v254, 42
	s_branch .LBB0_1549
